# nt hint also on norm-phase residual-stream reads and split-K partial reads
# speedup vs baseline: 1.0081x; 1.0030x over previous
.LBB0_151:
	s_andn2_b64 vcc, exec, s[14:15]
	s_cbranch_vccnz .LBB0_153
	s_lshl_b64 s[14:15], s[12:13], 12
	s_add_u32 s14, s18, s14
	s_addc_u32 s15, s7, s15
	s_waitcnt vmcnt(0)
	v_lshlrev_b32_e32 v14, 1, v130
	global_load_dwordx4 v[2:5], v14, s[14:15] nt
	global_load_dwordx4 v[6:9], v14, s[14:15] offset:1024 nt
	global_load_dwordx4 v[10:13], v14, s[14:15] offset:2048 nt
	global_load_dwordx4 v[34:37], v14, s[14:15] offset:3072 nt
	s_waitcnt vmcnt(3)
	v_lshlrev_b32_e32 v30, 16, v2
	v_and_b32_e32 v31, 0xffff0000, v2
	v_lshlrev_b32_e32 v32, 16, v3
	v_and_b32_e32 v33, 0xffff0000, v3
	v_lshlrev_b32_e32 v26, 16, v4
	v_and_b32_e32 v27, 0xffff0000, v4
	v_lshlrev_b32_e32 v28, 16, v5
	v_and_b32_e32 v29, 0xffff0000, v5
	s_waitcnt vmcnt(2)
	v_lshlrev_b32_e32 v22, 16, v6
	v_and_b32_e32 v23, 0xffff0000, v6
	v_lshlrev_b32_e32 v24, 16, v7
	v_and_b32_e32 v25, 0xffff0000, v7
	v_lshlrev_b32_e32 v18, 16, v8
	v_and_b32_e32 v19, 0xffff0000, v8
	v_lshlrev_b32_e32 v20, 16, v9
	v_and_b32_e32 v21, 0xffff0000, v9
	s_waitcnt vmcnt(1)
	v_lshlrev_b32_e32 v14, 16, v10
	v_and_b32_e32 v15, 0xffff0000, v10
	v_lshlrev_b32_e32 v16, 16, v11
	v_and_b32_e32 v17, 0xffff0000, v11
	v_lshlrev_b32_e32 v10, 16, v12
	v_and_b32_e32 v11, 0xffff0000, v12
	v_lshlrev_b32_e32 v12, 16, v13
	v_and_b32_e32 v13, 0xffff0000, v13
	s_waitcnt vmcnt(0)
	v_lshlrev_b32_e32 v6, 16, v34
	v_and_b32_e32 v7, 0xffff0000, v34
	v_lshlrev_b32_e32 v8, 16, v35
	v_and_b32_e32 v9, 0xffff0000, v35
	v_lshlrev_b32_e32 v2, 16, v36
	v_and_b32_e32 v3, 0xffff0000, v36
	v_lshlrev_b32_e32 v4, 16, v37
	v_and_b32_e32 v5, 0xffff0000, v37
.LBB0_153:
	s_ashr_i32 s7, s12, 10
	s_add_i32 s7, s7, 1
	s_and_b64 s[12:13], s[4:5], exec
	s_cselect_b32 s7, s7, 0
	s_and_b64 s[14:15], s[10:11], s[4:5]
	v_cndmask_b32_e64 v34, 0, 1, s[14:15]
	s_mul_hi_i32 s13, s7, 0x3000
	v_cmp_ne_u32_e64 s[4:5], 1, v34
	s_andn2_b64 vcc, exec, s[14:15]
	s_mul_i32 s12, s7, 0x3000
	s_cbranch_vccnz .LBB0_155
	s_lshl_b64 s[14:15], s[46:47], 12
	v_lshl_add_u64 v[70:71], v[138:139], 0, s[14:15]
	s_mov_b32 s7, 0x800000
	v_add_co_u32_e32 v72, vcc, s7, v70
	s_mov_b32 s7, 0x1000000
	s_nop 0
	v_addc_co_u32_e32 v73, vcc, 0, v71, vcc
	v_add_co_u32_e32 v74, vcc, s7, v70
	global_load_dwordx4 v[50:53], v[70:71], off nt
	global_load_dwordx4 v[54:57], v[72:73], off nt
	v_addc_co_u32_e32 v75, vcc, 0, v71, vcc
	global_load_dwordx4 v[58:61], v[74:75], off nt
	s_mov_b32 s7, 0x1800000
	v_add_co_u32_e32 v76, vcc, s7, v70
	s_lshl_b64 s[14:15], s[12:13], 2
	s_nop 0
	v_addc_co_u32_e32 v77, vcc, 0, v71, vcc
	global_load_dwordx4 v[62:65], v[76:77], off nt
	global_load_dwordx4 v[46:49], v[70:71], off offset:1024 nt
	global_load_dwordx4 v[34:37], v[72:73], off offset:1024 nt
	global_load_dwordx4 v[38:41], v[74:75], off offset:1024 nt
	s_add_u32 s14, s8, s14
	s_addc_u32 s15, s9, s15
	global_load_dwordx4 v[42:45], v[76:77], off offset:1024 nt
	s_waitcnt vmcnt(0)
	v_and_b32_e32 v66, 0xffff0000, v50
	v_and_b32_e32 v68, 0xffff0000, v54
	v_and_b32_e32 v78, 0xffff0000, v55
	v_lshlrev_b32_e32 v50, 16, v50
	v_and_b32_e32 v67, 0xffff0000, v58
	v_lshlrev_b32_e32 v54, 16, v54
	v_and_b32_e32 v69, 0xffff0000, v62
	v_pk_add_f32 v[66:67], v[66:67], v[68:69]
	v_and_b32_e32 v68, 0xffff0000, v51
	v_and_b32_e32 v69, 0xffff0000, v59
	v_and_b32_e32 v79, 0xffff0000, v63
	v_pk_add_f32 v[68:69], v[68:69], v[78:79]
	v_add_f32_e32 v78, v54, v50
	v_lshlrev_b32_e32 v50, 16, v58
	v_lshlrev_b32_e32 v54, 16, v62
	v_add_f32_e32 v80, v54, v50
	v_lshlrev_b32_e32 v50, 16, v51
	v_lshlrev_b32_e32 v51, 16, v55
	v_add_f32_e32 v50, v51, v50
	v_lshlrev_b32_e32 v51, 16, v59
	v_lshlrev_b32_e32 v54, 16, v63
	v_mov_b32_e32 v79, v66
	v_mov_b32_e32 v81, v67
	v_add_f32_e32 v54, v54, v51
	v_mov_b32_e32 v51, v68
	v_mov_b32_e32 v55, v69
	global_load_dwordx4 v[66:69], v0, s[14:15]
	v_pk_add_f32 v[58:59], v[78:79], v[80:81]
	v_pk_add_f32 v[50:51], v[50:51], v[54:55]
	v_lshlrev_b32_e32 v62, 16, v60
	v_lshlrev_b32_e32 v63, 16, v57
	v_and_b32_e32 v54, 0xffff0000, v56
	v_and_b32_e32 v55, 0xffff0000, v64
	v_lshlrev_b32_e32 v64, 16, v64
	v_add_f32_e32 v62, v64, v62
	v_lshlrev_b32_e32 v79, 16, v41
	v_lshlrev_b32_e32 v81, 16, v37
	v_lshlrev_b32_e32 v78, 16, v49
	s_waitcnt vmcnt(0)
	v_pk_fma_f32 v[30:31], v[66:67], v[58:59], v[30:31]
	v_pk_fma_f32 v[32:33], v[68:69], v[50:51], v[32:33]
	v_lshlrev_b32_e32 v58, 16, v52
	v_lshlrev_b32_e32 v59, 16, v53
	v_and_b32_e32 v50, 0xffff0000, v52
	v_and_b32_e32 v52, 0xffff0000, v53
	v_and_b32_e32 v51, 0xffff0000, v60
	v_and_b32_e32 v53, 0xffff0000, v61
	v_lshlrev_b32_e32 v60, 16, v56
	v_and_b32_e32 v56, 0xffff0000, v57
	v_and_b32_e32 v57, 0xffff0000, v65
	v_pk_add_f32 v[54:55], v[50:51], v[54:55]
	v_pk_add_f32 v[56:57], v[52:53], v[56:57]
	global_load_dwordx4 v[50:53], v0, s[14:15] offset:16
	v_lshlrev_b32_e32 v61, 16, v61
	v_lshlrev_b32_e32 v65, 16, v65
	v_add_f32_e32 v58, v60, v58
	v_add_f32_e32 v60, v63, v59
	v_add_f32_e32 v64, v65, v61
	v_mov_b32_e32 v59, v54
	v_mov_b32_e32 v63, v55
	v_mov_b32_e32 v61, v56
	v_mov_b32_e32 v65, v57
	global_load_dwordx4 v[54:57], v0, s[14:15] offset:2048
	v_pk_add_f32 v[58:59], v[58:59], v[62:63]
	v_pk_add_f32 v[60:61], v[60:61], v[64:65]
	global_load_dwordx4 v[62:65], v[76:77], off offset:2048 nt
	global_load_dwordx4 v[66:69], v0, s[14:15] offset:2064
	v_lshlrev_b32_e32 v80, 16, v45
	s_waitcnt vmcnt(3)
	v_pk_fma_f32 v[26:27], v[50:51], v[58:59], v[26:27]
	v_pk_fma_f32 v[28:29], v[52:53], v[60:61], v[28:29]
	v_and_b32_e32 v53, 0xffff0000, v38
	v_and_b32_e32 v52, 0xffff0000, v46
	v_and_b32_e32 v59, 0xffff0000, v42
	v_and_b32_e32 v58, 0xffff0000, v34
	v_lshlrev_b32_e32 v50, 16, v34
	v_pk_add_f32 v[52:53], v[52:53], v[58:59]
	v_and_b32_e32 v59, 0xffff0000, v39
	v_and_b32_e32 v58, 0xffff0000, v47
	v_and_b32_e32 v61, 0xffff0000, v43
	v_and_b32_e32 v60, 0xffff0000, v35
	v_lshlrev_b32_e32 v34, 16, v38
	v_lshlrev_b32_e32 v38, 16, v42
	v_pk_add_f32 v[58:59], v[58:59], v[60:61]
	v_add_f32_e32 v60, v38, v34
	v_lshlrev_b32_e32 v34, 16, v35
	v_lshlrev_b32_e32 v35, 16, v47
	v_lshlrev_b32_e32 v51, 16, v46
	v_add_f32_e32 v34, v34, v35
	v_lshlrev_b32_e32 v35, 16, v39
	v_lshlrev_b32_e32 v38, 16, v43
	v_add_f32_e32 v50, v50, v51
	v_mov_b32_e32 v51, v52
	v_mov_b32_e32 v61, v53
	v_add_f32_e32 v38, v38, v35
	v_mov_b32_e32 v35, v58
	v_mov_b32_e32 v39, v59
	v_pk_add_f32 v[46:47], v[50:51], v[60:61]
	v_pk_add_f32 v[34:35], v[34:35], v[38:39]
	s_waitcnt vmcnt(2)
	v_pk_fma_f32 v[22:23], v[54:55], v[46:47], v[22:23]
	global_load_dwordx4 v[50:53], v[70:71], off offset:2048 nt
	v_pk_fma_f32 v[24:25], v[56:57], v[34:35], v[24:25]
	global_load_dwordx4 v[54:57], v[72:73], off offset:2048 nt
	global_load_dwordx4 v[58:61], v[74:75], off offset:2048 nt
	v_and_b32_e32 v34, 0xffff0000, v48
	v_lshlrev_b32_e32 v47, 16, v40
	v_and_b32_e32 v35, 0xffff0000, v40
	v_and_b32_e32 v39, 0xffff0000, v41
	v_and_b32_e32 v41, 0xffff0000, v44
	v_and_b32_e32 v40, 0xffff0000, v36
	v_lshlrev_b32_e32 v46, 16, v48
	v_lshlrev_b32_e32 v48, 16, v44
	v_lshlrev_b32_e32 v44, 16, v36
	v_pk_add_f32 v[34:35], v[34:35], v[40:41]
	v_and_b32_e32 v38, 0xffff0000, v49
	v_and_b32_e32 v43, 0xffff0000, v45
	v_and_b32_e32 v42, 0xffff0000, v37
	v_add_f32_e32 v36, v44, v46
	v_add_f32_e32 v40, v48, v47
	v_mov_b32_e32 v37, v34
	v_mov_b32_e32 v41, v35
	v_pk_add_f32 v[38:39], v[38:39], v[42:43]
	v_pk_add_f32 v[40:41], v[36:37], v[40:41]
	global_load_dwordx4 v[46:49], v[70:71], off offset:3072 nt
	s_waitcnt vmcnt(4)
	v_pk_fma_f32 v[18:19], v[66:67], v[40:41], v[18:19]
	v_add_f32_e32 v66, v81, v78
	v_add_f32_e32 v70, v80, v79
	v_mov_b32_e32 v67, v38
	v_mov_b32_e32 v71, v39
	v_pk_add_f32 v[66:67], v[66:67], v[70:71]
	global_load_dwordx4 v[34:37], v[72:73], off offset:3072 nt
	v_pk_fma_f32 v[20:21], v[68:69], v[66:67], v[20:21]
	global_load_dwordx4 v[42:45], v[74:75], off offset:3072 nt
	v_and_b32_e32 v71, 0xffff0000, v62
	v_and_b32_e32 v73, 0xffff0000, v63
	global_load_dwordx4 v[38:41], v[76:77], off offset:3072 nt
	v_lshlrev_b32_e32 v75, 16, v65
	s_waitcnt vmcnt(6)
	v_lshlrev_b32_e32 v67, 16, v50
	s_waitcnt vmcnt(5)
	v_lshlrev_b32_e32 v66, 16, v54
	v_add_f32_e32 v68, v66, v67
	s_waitcnt vmcnt(4)
	v_and_b32_e32 v67, 0xffff0000, v58
	v_and_b32_e32 v66, 0xffff0000, v50
	v_and_b32_e32 v70, 0xffff0000, v54
	v_pk_add_f32 v[70:71], v[66:67], v[70:71]
	v_and_b32_e32 v67, 0xffff0000, v59
	v_and_b32_e32 v66, 0xffff0000, v51
	v_and_b32_e32 v72, 0xffff0000, v55
	v_lshlrev_b32_e32 v50, 16, v58
	v_lshlrev_b32_e32 v54, 16, v62
	v_pk_add_f32 v[66:67], v[66:67], v[72:73]
	v_add_f32_e32 v72, v54, v50
	v_mov_b32_e32 v69, v70
	v_mov_b32_e32 v73, v71
	v_pk_add_f32 v[68:69], v[68:69], v[72:73]
	global_load_dwordx4 v[70:73], v145, s[14:15]
	v_lshlrev_b32_e32 v50, 16, v55
	v_lshlrev_b32_e32 v51, 16, v51
	v_add_f32_e32 v50, v50, v51
	v_lshlrev_b32_e32 v51, 16, v59
	v_lshlrev_b32_e32 v54, 16, v63
	v_add_f32_e32 v54, v54, v51
	v_mov_b32_e32 v51, v66
	v_mov_b32_e32 v55, v67
	v_pk_add_f32 v[50:51], v[50:51], v[54:55]
	v_and_b32_e32 v54, 0xffff0000, v52
	v_and_b32_e32 v58, 0xffff0000, v53
	v_and_b32_e32 v55, 0xffff0000, v60
	v_and_b32_e32 v59, 0xffff0000, v61
	v_lshlrev_b32_e32 v74, 16, v61
	v_and_b32_e32 v61, 0xffff0000, v64
	v_and_b32_e32 v63, 0xffff0000, v65
	v_lshlrev_b32_e32 v65, 16, v57
	v_and_b32_e32 v62, 0xffff0000, v57
	v_pk_add_f32 v[58:59], v[58:59], v[62:63]
	s_waitcnt vmcnt(0)
	v_pk_fma_f32 v[14:15], v[70:71], v[68:69], v[14:15]
	global_load_dwordx4 v[66:69], v145, s[14:15] offset:16
	v_pk_fma_f32 v[16:17], v[72:73], v[50:51], v[16:17]
	v_lshlrev_b32_e32 v70, 16, v52
	v_lshlrev_b32_e32 v71, 16, v53
	v_lshlrev_b32_e32 v72, 16, v60
	v_and_b32_e32 v60, 0xffff0000, v56
	global_load_dwordx4 v[50:53], v146, s[14:15]
	v_lshlrev_b32_e32 v73, 16, v64
	v_lshlrev_b32_e32 v64, 16, v56
	v_pk_add_f32 v[60:61], v[54:55], v[60:61]
	global_load_dwordx4 v[54:57], v146, s[14:15] offset:16
	v_add_f32_e32 v62, v64, v70
	v_add_f32_e32 v64, v73, v72
	v_add_f32_e32 v70, v65, v71
	v_add_f32_e32 v72, v75, v74
	v_mov_b32_e32 v63, v60
	v_mov_b32_e32 v65, v61
	v_mov_b32_e32 v71, v58
	v_mov_b32_e32 v73, v59
	v_pk_add_f32 v[60:61], v[62:63], v[64:65]
	v_pk_add_f32 v[58:59], v[70:71], v[72:73]
	v_and_b32_e32 v65, 0xffff0000, v38
	v_and_b32_e32 v64, 0xffff0000, v34
	v_and_b32_e32 v63, 0xffff0000, v42
	v_and_b32_e32 v62, 0xffff0000, v46
	v_pk_add_f32 v[62:63], v[62:63], v[64:65]
	s_waitcnt vmcnt(2)
	v_pk_fma_f32 v[10:11], v[66:67], v[60:61], v[10:11]
	v_pk_fma_f32 v[12:13], v[68:69], v[58:59], v[12:13]
	v_lshlrev_b32_e32 v58, 16, v34
	v_lshlrev_b32_e32 v59, 16, v46
	v_lshlrev_b32_e32 v60, 16, v38
	v_lshlrev_b32_e32 v34, 16, v35
	v_lshlrev_b32_e32 v38, 16, v47
	v_add_f32_e32 v58, v58, v59
	v_lshlrev_b32_e32 v59, 16, v42
	v_add_f32_e32 v34, v34, v38
	v_lshlrev_b32_e32 v38, 16, v43
	v_lshlrev_b32_e32 v42, 16, v39
	v_add_f32_e32 v38, v42, v38
	v_and_b32_e32 v43, 0xffff0000, v43
	v_and_b32_e32 v42, 0xffff0000, v47
	v_and_b32_e32 v47, 0xffff0000, v39
	v_and_b32_e32 v46, 0xffff0000, v35
	v_pk_add_f32 v[42:43], v[42:43], v[46:47]
	v_lshlrev_b32_e32 v35, 16, v48
	v_lshlrev_b32_e32 v47, 16, v36
	v_add_f32_e32 v64, v47, v35
	v_lshlrev_b32_e32 v35, 16, v44
	v_and_b32_e32 v47, 0xffff0000, v44
	v_lshlrev_b32_e32 v44, 16, v40
	v_lshlrev_b32_e32 v39, 16, v49
	v_add_f32_e32 v44, v44, v35
	v_lshlrev_b32_e32 v35, 16, v37
	v_and_b32_e32 v46, 0xffff0000, v48
	v_and_b32_e32 v48, 0xffff0000, v49
	v_and_b32_e32 v49, 0xffff0000, v45
	v_lshlrev_b32_e32 v45, 16, v45
	v_and_b32_e32 v67, 0xffff0000, v40
	v_and_b32_e32 v66, 0xffff0000, v36
	v_add_f32_e32 v36, v35, v39
	v_lshlrev_b32_e32 v35, 16, v41
	v_pk_add_f32 v[46:47], v[46:47], v[66:67]
	v_add_f32_e32 v40, v35, v45
	v_and_b32_e32 v67, 0xffff0000, v41
	v_and_b32_e32 v66, 0xffff0000, v37
	v_mov_b32_e32 v35, v42
	v_mov_b32_e32 v39, v43
	v_pk_add_f32 v[48:49], v[48:49], v[66:67]
	v_pk_add_f32 v[34:35], v[34:35], v[38:39]
	v_mov_b32_e32 v65, v46
	v_mov_b32_e32 v45, v47
	v_add_f32_e32 v60, v60, v59
	v_mov_b32_e32 v59, v62
	v_mov_b32_e32 v61, v63
	s_waitcnt vmcnt(1)
	v_pk_fma_f32 v[8:9], v[52:53], v[34:35], v[8:9]
	v_pk_add_f32 v[34:35], v[64:65], v[44:45]
	v_mov_b32_e32 v37, v48
	v_mov_b32_e32 v41, v49
	v_pk_add_f32 v[58:59], v[58:59], v[60:61]
	s_waitcnt vmcnt(0)
	v_pk_fma_f32 v[2:3], v[54:55], v[34:35], v[2:3]
	v_pk_add_f32 v[34:35], v[36:37], v[40:41]
	v_pk_fma_f32 v[6:7], v[50:51], v[58:59], v[6:7]
	v_pk_fma_f32 v[4:5], v[56:57], v[34:35], v[4:5]

.LBB0_1032:
	s_andn2_b64 vcc, exec, s[12:13]
	s_cbranch_vccnz .LBB0_1034
	s_and_b64 s[12:13], s[4:5], exec
	s_cselect_b32 s3, s7, s1
	s_cselect_b32 s18, s6, s0
	s_lshl_b64 s[12:13], s[8:9], 12
	s_add_u32 s12, s18, s12
	s_addc_u32 s13, s3, s13
	s_waitcnt vmcnt(0)
	v_lshlrev_b32_e32 v14, 1, v130
	global_load_dwordx4 v[2:5], v14, s[12:13] nt
	global_load_dwordx4 v[6:9], v14, s[12:13] offset:1024 nt
	global_load_dwordx4 v[10:13], v14, s[12:13] offset:2048 nt
	global_load_dwordx4 v[34:37], v14, s[12:13] offset:3072 nt
	s_waitcnt vmcnt(3)
	v_lshlrev_b32_e32 v30, 16, v2
	v_and_b32_e32 v31, 0xffff0000, v2
	v_lshlrev_b32_e32 v32, 16, v3
	v_and_b32_e32 v33, 0xffff0000, v3
	v_lshlrev_b32_e32 v26, 16, v4
	v_and_b32_e32 v27, 0xffff0000, v4
	v_lshlrev_b32_e32 v28, 16, v5
	v_and_b32_e32 v29, 0xffff0000, v5
	s_waitcnt vmcnt(2)
	v_lshlrev_b32_e32 v22, 16, v6
	v_and_b32_e32 v23, 0xffff0000, v6
	v_lshlrev_b32_e32 v24, 16, v7
	v_and_b32_e32 v25, 0xffff0000, v7
	v_lshlrev_b32_e32 v18, 16, v8
	v_and_b32_e32 v19, 0xffff0000, v8
	v_lshlrev_b32_e32 v20, 16, v9
	v_and_b32_e32 v21, 0xffff0000, v9
	s_waitcnt vmcnt(1)
	v_lshlrev_b32_e32 v14, 16, v10
	v_and_b32_e32 v15, 0xffff0000, v10
	v_lshlrev_b32_e32 v16, 16, v11
	v_and_b32_e32 v17, 0xffff0000, v11
	v_lshlrev_b32_e32 v10, 16, v12
	v_and_b32_e32 v11, 0xffff0000, v12
	v_lshlrev_b32_e32 v12, 16, v13
	v_and_b32_e32 v13, 0xffff0000, v13
	s_waitcnt vmcnt(0)
	v_lshlrev_b32_e32 v6, 16, v34
	v_and_b32_e32 v7, 0xffff0000, v34
	v_lshlrev_b32_e32 v8, 16, v35
	v_and_b32_e32 v9, 0xffff0000, v35
	v_lshlrev_b32_e32 v2, 16, v36
	v_and_b32_e32 v3, 0xffff0000, v36
	v_lshlrev_b32_e32 v4, 16, v37
	v_and_b32_e32 v5, 0xffff0000, v37
.LBB0_1034:
	s_ashr_i32 s3, s8, 10
	s_add_i32 s3, s3, 1
	s_and_b64 s[4:5], s[4:5], exec
	s_cselect_b32 s3, 0, s3
	v_cndmask_b32_e64 v34, 0, 1, s[10:11]
	s_mul_hi_i32 s9, s3, 0x3000
	v_cmp_ne_u32_e64 s[4:5], 1, v34
	s_andn2_b64 vcc, exec, s[10:11]
	s_mul_i32 s8, s3, 0x3000
	s_cbranch_vccnz .LBB0_1036
	s_lshl_b64 s[10:11], s[46:47], 12
	v_lshl_add_u64 v[34:35], v[140:141], 0, s[10:11]
	s_mov_b32 s3, 0x800000
	v_add_co_u32_e32 v46, vcc, s3, v34
	s_mov_b32 s3, 0x1000000
	s_nop 0
	v_addc_co_u32_e32 v47, vcc, 0, v35, vcc
	v_add_co_u32_e32 v50, vcc, s3, v34
	s_mov_b32 s3, 0x1800000
	s_nop 0
	v_addc_co_u32_e32 v51, vcc, 0, v35, vcc
	v_add_co_u32_e32 v52, vcc, s3, v34
	global_load_dwordx4 v[82:85], v[34:35], off nt
	global_load_dwordx4 v[86:89], v[46:47], off nt
	v_addc_co_u32_e32 v53, vcc, 0, v35, vcc
	global_load_dwordx4 v[90:93], v[50:51], off nt
	global_load_dwordx4 v[94:97], v[52:53], off nt
	s_lshl_b64 s[10:11], s[8:9], 2
	s_add_u32 s10, s14, s10
	s_addc_u32 s11, s15, s11
	global_load_dwordx4 v[98:101], v0, s[10:11]
	global_load_dwordx4 v[102:105], v0, s[10:11] offset:16
	global_load_dwordx4 v[106:109], v[46:47], off offset:1024 nt
	global_load_dwordx4 v[110:113], v[34:35], off offset:1024 nt
	global_load_dwordx4 v[114:117], v[50:51], off offset:1024 nt
	global_load_dwordx4 v[118:121], v[52:53], off offset:1024 nt
	global_load_dwordx4 v[66:69], v[34:35], off offset:2048 nt
	global_load_dwordx4 v[42:45], v[34:35], off offset:3072 nt
	global_load_dwordx4 v[122:125], v0, s[10:11] offset:2064
	global_load_dwordx4 v[126:129], v0, s[10:11] offset:2048
	global_load_dwordx4 v[58:61], v147, s[10:11] offset:16
	global_load_dwordx4 v[62:65], v147, s[10:11]
	s_nop 0
	global_load_dwordx4 v[34:37], v148, s[10:11] offset:16
	global_load_dwordx4 v[38:41], v148, s[10:11]
	global_load_dwordx4 v[70:73], v[46:47], off offset:2048 nt
	s_nop 0
	global_load_dwordx4 v[46:49], v[46:47], off offset:3072 nt
	s_nop 0
	global_load_dwordx4 v[78:81], v[50:51], off offset:2048 nt
	global_load_dwordx4 v[54:57], v[50:51], off offset:3072 nt
	global_load_dwordx4 v[74:77], v[52:53], off offset:2048 nt
	s_nop 0
	global_load_dwordx4 v[50:53], v[52:53], off offset:3072 nt
	s_waitcnt vmcnt(0)
	v_lshlrev_b32_e32 v149, 16, v82
	v_lshlrev_b32_e32 v151, 16, v83
	v_and_b32_e32 v150, 0xffff0000, v83
	v_lshlrev_b32_e32 v153, 16, v84
	v_lshlrev_b32_e32 v155, 16, v85
	v_and_b32_e32 v152, 0xffff0000, v85
	v_lshlrev_b32_e32 v83, 16, v86
	v_lshlrev_b32_e32 v85, 16, v87
	v_and_b32_e32 v154, 0xffff0000, v87
	v_lshlrev_b32_e32 v87, 16, v88
	v_and_b32_e32 v82, 0xffff0000, v82
	v_and_b32_e32 v86, 0xffff0000, v86
	v_lshlrev_b32_e32 v157, 16, v89
	v_add_f32_e32 v158, v83, v149
	v_and_b32_e32 v83, 0xffff0000, v90
	v_add_f32_e32 v160, v87, v153
	v_and_b32_e32 v87, 0xffff0000, v94
	v_lshlrev_b32_e32 v149, 16, v90
	v_add_f32_e32 v90, v85, v151
	v_lshlrev_b32_e32 v159, 16, v91
	v_and_b32_e32 v151, 0xffff0000, v91
	v_lshlrev_b32_e32 v91, 16, v92
	v_and_b32_e32 v85, 0xffff0000, v92
	v_add_f32_e32 v92, v157, v155
	v_lshlrev_b32_e32 v161, 16, v93
	v_and_b32_e32 v153, 0xffff0000, v93
	v_lshlrev_b32_e32 v93, 16, v94
	v_lshlrev_b32_e32 v162, 16, v95
	v_and_b32_e32 v155, 0xffff0000, v95
	v_lshlrev_b32_e32 v95, 16, v96
	v_pk_add_f32 v[82:83], v[82:83], v[86:87]
	v_and_b32_e32 v84, 0xffff0000, v84
	v_and_b32_e32 v88, 0xffff0000, v88
	v_and_b32_e32 v156, 0xffff0000, v89
	v_and_b32_e32 v89, 0xffff0000, v96
	v_lshlrev_b32_e32 v163, 16, v97
	v_and_b32_e32 v157, 0xffff0000, v97
	v_add_f32_e32 v94, v93, v149
	v_add_f32_e32 v86, v162, v159
	v_pk_add_f32 v[96:97], v[150:151], v[154:155]
	v_add_f32_e32 v150, v95, v91
	v_mov_b32_e32 v159, v82
	v_mov_b32_e32 v95, v83
	v_pk_add_f32 v[84:85], v[84:85], v[88:89]
	v_pk_add_f32 v[82:83], v[158:159], v[94:95]
	v_mov_b32_e32 v91, v96
	v_mov_b32_e32 v87, v97
	v_add_f32_e32 v88, v163, v161
	v_pk_add_f32 v[152:153], v[152:153], v[156:157]
	v_pk_fma_f32 v[30:31], v[98:99], v[82:83], v[30:31]
	v_pk_add_f32 v[82:83], v[90:91], v[86:87]
	v_mov_b32_e32 v161, v84
	v_mov_b32_e32 v151, v85
	v_pk_fma_f32 v[32:33], v[100:101], v[82:83], v[32:33]
	v_pk_add_f32 v[82:83], v[160:161], v[150:151]
	v_mov_b32_e32 v93, v152
	v_mov_b32_e32 v89, v153
	v_pk_fma_f32 v[26:27], v[102:103], v[82:83], v[26:27]
	v_pk_add_f32 v[82:83], v[92:93], v[88:89]
	v_lshlrev_b32_e32 v84, 16, v118
	v_pk_fma_f32 v[28:29], v[104:105], v[82:83], v[28:29]
	v_lshlrev_b32_e32 v82, 16, v106
	v_lshlrev_b32_e32 v83, 16, v110
	v_add_f32_e32 v82, v82, v83
	v_lshlrev_b32_e32 v83, 16, v114
	v_add_f32_e32 v84, v84, v83
	v_and_b32_e32 v87, 0xffff0000, v114
	v_and_b32_e32 v86, 0xffff0000, v110
	v_and_b32_e32 v89, 0xffff0000, v118
	v_and_b32_e32 v88, 0xffff0000, v106
	v_lshlrev_b32_e32 v83, 16, v107
	v_lshlrev_b32_e32 v85, 16, v111
	v_pk_add_f32 v[86:87], v[86:87], v[88:89]
	v_add_f32_e32 v88, v83, v85
	v_lshlrev_b32_e32 v83, 16, v115
	v_lshlrev_b32_e32 v85, 16, v119
	v_add_f32_e32 v90, v85, v83
	v_and_b32_e32 v93, 0xffff0000, v115
	v_and_b32_e32 v92, 0xffff0000, v111
	v_and_b32_e32 v95, 0xffff0000, v119
	v_and_b32_e32 v94, 0xffff0000, v107
	v_lshlrev_b32_e32 v83, 16, v108
	v_lshlrev_b32_e32 v85, 16, v112
	v_pk_add_f32 v[92:93], v[92:93], v[94:95]
	v_add_f32_e32 v94, v83, v85
	v_lshlrev_b32_e32 v83, 16, v116
	v_lshlrev_b32_e32 v85, 16, v120
	v_add_f32_e32 v96, v85, v83
	v_and_b32_e32 v99, 0xffff0000, v116
	v_and_b32_e32 v98, 0xffff0000, v112
	v_and_b32_e32 v101, 0xffff0000, v120
	v_and_b32_e32 v100, 0xffff0000, v108
	v_lshlrev_b32_e32 v83, 16, v109
	v_lshlrev_b32_e32 v85, 16, v113
	v_pk_add_f32 v[98:99], v[98:99], v[100:101]
	v_add_f32_e32 v100, v83, v85
	v_lshlrev_b32_e32 v83, 16, v117
	v_lshlrev_b32_e32 v85, 16, v121
	v_add_f32_e32 v102, v85, v83
	v_mov_b32_e32 v83, v86
	v_mov_b32_e32 v85, v87
	v_and_b32_e32 v105, 0xffff0000, v117
	v_and_b32_e32 v104, 0xffff0000, v113
	v_and_b32_e32 v107, 0xffff0000, v121
	v_and_b32_e32 v106, 0xffff0000, v109
	v_pk_add_f32 v[82:83], v[82:83], v[84:85]
	v_mov_b32_e32 v89, v92
	v_mov_b32_e32 v91, v93
	v_pk_add_f32 v[104:105], v[104:105], v[106:107]
	v_pk_fma_f32 v[22:23], v[126:127], v[82:83], v[22:23]
	v_pk_add_f32 v[82:83], v[88:89], v[90:91]
	v_mov_b32_e32 v95, v98
	v_mov_b32_e32 v97, v99
	v_pk_fma_f32 v[24:25], v[128:129], v[82:83], v[24:25]
	v_pk_add_f32 v[82:83], v[94:95], v[96:97]
	v_mov_b32_e32 v101, v104
	v_mov_b32_e32 v103, v105
	v_pk_fma_f32 v[18:19], v[122:123], v[82:83], v[18:19]
	v_pk_add_f32 v[82:83], v[100:101], v[102:103]
	v_and_b32_e32 v86, 0xffff0000, v66
	v_pk_fma_f32 v[20:21], v[124:125], v[82:83], v[20:21]
	v_lshlrev_b32_e32 v82, 16, v70
	v_lshlrev_b32_e32 v83, 16, v66
	v_and_b32_e32 v88, 0xffff0000, v70
	v_lshlrev_b32_e32 v66, 16, v71
	v_lshlrev_b32_e32 v70, 16, v67
	v_lshlrev_b32_e32 v84, 16, v74
	v_and_b32_e32 v89, 0xffff0000, v74
	v_add_f32_e32 v66, v66, v70
	v_lshlrev_b32_e32 v70, 16, v79
	v_lshlrev_b32_e32 v74, 16, v75
	v_add_f32_e32 v82, v82, v83
	v_lshlrev_b32_e32 v83, 16, v78
	v_and_b32_e32 v87, 0xffff0000, v78
	v_add_f32_e32 v70, v74, v70
	v_and_b32_e32 v79, 0xffff0000, v79
	v_and_b32_e32 v78, 0xffff0000, v67
	v_and_b32_e32 v75, 0xffff0000, v75
	v_and_b32_e32 v74, 0xffff0000, v71
	v_lshlrev_b32_e32 v67, 16, v72
	v_lshlrev_b32_e32 v71, 16, v68
	v_pk_add_f32 v[74:75], v[78:79], v[74:75]
	v_add_f32_e32 v78, v67, v71
	v_lshlrev_b32_e32 v67, 16, v80
	v_lshlrev_b32_e32 v71, 16, v76
	v_pk_add_f32 v[86:87], v[86:87], v[88:89]
	v_add_f32_e32 v88, v71, v67
	v_and_b32_e32 v90, 0xffff0000, v68
	v_lshlrev_b32_e32 v67, 16, v73
	v_lshlrev_b32_e32 v68, 16, v69
	v_add_f32_e32 v84, v84, v83
	v_and_b32_e32 v91, 0xffff0000, v80
	v_and_b32_e32 v93, 0xffff0000, v76
	v_and_b32_e32 v92, 0xffff0000, v72
	v_add_f32_e32 v68, v67, v68
	v_lshlrev_b32_e32 v67, 16, v81
	v_lshlrev_b32_e32 v71, 16, v77
	v_and_b32_e32 v81, 0xffff0000, v81
	v_and_b32_e32 v80, 0xffff0000, v69
	v_and_b32_e32 v77, 0xffff0000, v77
	v_and_b32_e32 v76, 0xffff0000, v73
	v_mov_b32_e32 v83, v86
	v_mov_b32_e32 v85, v87
	v_pk_add_f32 v[90:91], v[90:91], v[92:93]
	v_add_f32_e32 v72, v71, v67
	v_pk_add_f32 v[76:77], v[80:81], v[76:77]
	v_pk_add_f32 v[80:81], v[82:83], v[84:85]
	v_mov_b32_e32 v67, v74
	v_mov_b32_e32 v71, v75
	v_pk_fma_f32 v[14:15], v[62:63], v[80:81], v[14:15]
	v_pk_add_f32 v[62:63], v[66:67], v[70:71]
	v_mov_b32_e32 v79, v90
	v_mov_b32_e32 v89, v91
	v_pk_fma_f32 v[16:17], v[64:65], v[62:63], v[16:17]
	v_pk_add_f32 v[62:63], v[78:79], v[88:89]
	v_mov_b32_e32 v69, v76
	v_mov_b32_e32 v73, v77
	v_pk_fma_f32 v[10:11], v[58:59], v[62:63], v[10:11]
	v_pk_add_f32 v[58:59], v[68:69], v[72:73]
	v_and_b32_e32 v62, 0xffff0000, v42
	v_pk_fma_f32 v[12:13], v[60:61], v[58:59], v[12:13]
	v_lshlrev_b32_e32 v58, 16, v46
	v_lshlrev_b32_e32 v59, 16, v42
	v_and_b32_e32 v64, 0xffff0000, v46
	v_lshlrev_b32_e32 v42, 16, v47
	v_lshlrev_b32_e32 v46, 16, v43
	v_lshlrev_b32_e32 v60, 16, v50
	v_and_b32_e32 v65, 0xffff0000, v50
	v_add_f32_e32 v42, v42, v46
	v_lshlrev_b32_e32 v46, 16, v55
	v_lshlrev_b32_e32 v50, 16, v51
	v_add_f32_e32 v58, v58, v59
	v_lshlrev_b32_e32 v59, 16, v54
	v_and_b32_e32 v63, 0xffff0000, v54
	v_add_f32_e32 v46, v50, v46
	v_and_b32_e32 v55, 0xffff0000, v55
	v_and_b32_e32 v54, 0xffff0000, v43
	v_and_b32_e32 v51, 0xffff0000, v51
	v_and_b32_e32 v50, 0xffff0000, v47
	v_lshlrev_b32_e32 v43, 16, v48
	v_lshlrev_b32_e32 v47, 16, v44
	v_pk_add_f32 v[50:51], v[54:55], v[50:51]
	v_add_f32_e32 v54, v43, v47
	v_lshlrev_b32_e32 v43, 16, v56
	v_lshlrev_b32_e32 v47, 16, v52
	v_pk_add_f32 v[62:63], v[62:63], v[64:65]
	v_add_f32_e32 v64, v47, v43
	v_and_b32_e32 v66, 0xffff0000, v44
	v_lshlrev_b32_e32 v43, 16, v49
	v_lshlrev_b32_e32 v44, 16, v45
	v_add_f32_e32 v60, v60, v59
	v_and_b32_e32 v67, 0xffff0000, v56
	v_and_b32_e32 v69, 0xffff0000, v52
	v_and_b32_e32 v68, 0xffff0000, v48
	v_add_f32_e32 v44, v43, v44
	v_lshlrev_b32_e32 v43, 16, v57
	v_lshlrev_b32_e32 v47, 16, v53
	v_and_b32_e32 v57, 0xffff0000, v57
	v_and_b32_e32 v56, 0xffff0000, v45
	v_and_b32_e32 v53, 0xffff0000, v53
	v_and_b32_e32 v52, 0xffff0000, v49
	v_mov_b32_e32 v59, v62
	v_mov_b32_e32 v61, v63
	v_pk_add_f32 v[66:67], v[66:67], v[68:69]
	v_add_f32_e32 v48, v47, v43
	v_pk_add_f32 v[52:53], v[56:57], v[52:53]
	v_pk_add_f32 v[56:57], v[58:59], v[60:61]
	v_mov_b32_e32 v43, v50
	v_mov_b32_e32 v47, v51
	v_pk_fma_f32 v[6:7], v[38:39], v[56:57], v[6:7]
	v_pk_add_f32 v[38:39], v[42:43], v[46:47]
	v_mov_b32_e32 v55, v66
	v_mov_b32_e32 v65, v67
	v_pk_fma_f32 v[8:9], v[40:41], v[38:39], v[8:9]
	v_pk_add_f32 v[38:39], v[54:55], v[64:65]
	v_mov_b32_e32 v45, v52
	v_mov_b32_e32 v49, v53
	v_pk_fma_f32 v[2:3], v[34:35], v[38:39], v[2:3]
	v_pk_add_f32 v[34:35], v[44:45], v[48:49]
	s_nop 0
	v_pk_fma_f32 v[4:5], v[36:37], v[34:35], v[4:5]

.LBB0_1230:
	global_load_dwordx4 v[0:3], v[52:53], off nt
	global_load_dwordx4 v[4:7], v[52:53], off offset:1024 nt
	global_load_dwordx4 v[8:11], v[52:53], off offset:2048 nt
	global_load_dwordx4 v[12:15], v[52:53], off offset:3072 nt
	s_cmpk_lt_i32 s2, 0x2000
	s_waitcnt vmcnt(0)
	v_and_b32_e32 v85, 0xffff0000, v0
	v_lshlrev_b32_e32 v84, 16, v0
	v_and_b32_e32 v87, 0xffff0000, v1
	v_lshlrev_b32_e32 v86, 16, v1
	v_and_b32_e32 v81, 0xffff0000, v2
	v_lshlrev_b32_e32 v80, 16, v2
	v_and_b32_e32 v83, 0xffff0000, v3
	v_lshlrev_b32_e32 v82, 16, v3
	v_lshlrev_b32_e32 v76, 16, v4
	v_and_b32_e32 v77, 0xffff0000, v4
	v_lshlrev_b32_e32 v78, 16, v5
	v_and_b32_e32 v79, 0xffff0000, v5
	v_lshlrev_b32_e32 v72, 16, v6
	v_and_b32_e32 v73, 0xffff0000, v6
	v_lshlrev_b32_e32 v74, 16, v7
	v_and_b32_e32 v75, 0xffff0000, v7
	v_lshlrev_b32_e32 v68, 16, v8
	v_and_b32_e32 v69, 0xffff0000, v8
	v_lshlrev_b32_e32 v70, 16, v9
	v_and_b32_e32 v71, 0xffff0000, v9
	v_lshlrev_b32_e32 v64, 16, v10
	v_and_b32_e32 v65, 0xffff0000, v10
	v_lshlrev_b32_e32 v66, 16, v11
	v_and_b32_e32 v67, 0xffff0000, v11
	v_lshlrev_b32_e32 v56, 16, v12
	v_and_b32_e32 v57, 0xffff0000, v12
	v_lshlrev_b32_e32 v60, 16, v13
	v_and_b32_e32 v61, 0xffff0000, v13
	v_lshlrev_b32_e32 v58, 16, v14
	v_and_b32_e32 v59, 0xffff0000, v14
	v_lshlrev_b32_e32 v62, 16, v15
	v_and_b32_e32 v63, 0xffff0000, v15
	s_cbranch_scc1 .LBB0_1229
	s_add_i32 s0, s2, 0xffffe000
	s_lshl_b64 s[6:7], s[0:1], 12
	v_lshl_add_u64 v[88:89], v[50:51], 0, s[6:7]
	v_add_co_u32_e32 v90, vcc, s3, v88
	global_load_dwordx4 v[4:7], v[88:89], off nt
	global_load_dwordx4 v[0:3], v[88:89], off offset:1024 nt
	v_addc_co_u32_e32 v91, vcc, 0, v89, vcc
	v_add_co_u32_e32 v92, vcc, s10, v88
	global_load_dwordx4 v[20:23], v[90:91], off nt
	s_nop 0
	v_addc_co_u32_e32 v93, vcc, 0, v89, vcc
	v_add_co_u32_e32 v94, vcc, s11, v88
	global_load_dwordx4 v[8:11], v[92:93], off nt
	s_nop 0
	v_addc_co_u32_e32 v95, vcc, 0, v89, vcc
	global_load_dwordx4 v[100:103], v[94:95], off nt
	s_lshr_b32 s0, s0, 10
	s_add_i32 s0, s0, 1
	s_mul_hi_u32 s7, s0, 0xc000
	s_mul_i32 s0, s0, 0xc000
	s_add_u32 s6, s8, s0
	s_addc_u32 s7, s9, s7
	global_load_dwordx4 v[104:107], v96, s[6:7]
	global_load_dwordx4 v[108:111], v96, s[6:7] offset:16
	global_load_dwordx4 v[24:27], v[90:91], off offset:1024 nt
	global_load_dwordx4 v[16:19], v[92:93], off offset:1024 nt
	global_load_dwordx4 v[12:15], v[94:95], off offset:1024 nt
	global_load_dwordx4 v[32:35], v96, s[6:7] offset:2048
	global_load_dwordx4 v[28:31], v[88:89], off offset:2048 nt
	global_load_dwordx4 v[36:39], v[90:91], off offset:2048 nt
	global_load_dwordx4 v[112:115], v96, s[6:7] offset:2064
	global_load_dwordx4 v[40:43], v[92:93], off offset:2048 nt
	global_load_dwordx4 v[116:119], v97, s[6:7]
	global_load_dwordx4 v[120:123], v[94:95], off offset:2048 nt
	s_waitcnt vmcnt(16)
	v_and_b32_e32 v125, 0xffff0000, v4
	v_lshlrev_b32_e32 v124, 16, v4
	v_and_b32_e32 v127, 0xffff0000, v5
	v_lshlrev_b32_e32 v126, 16, v5
	v_and_b32_e32 v5, 0xffff0000, v6
	v_lshlrev_b32_e32 v4, 16, v6
	v_and_b32_e32 v129, 0xffff0000, v7
	v_lshlrev_b32_e32 v128, 16, v7
	s_waitcnt vmcnt(14)
	v_and_b32_e32 v131, 0xffff0000, v20
	v_lshlrev_b32_e32 v130, 16, v20
	v_and_b32_e32 v133, 0xffff0000, v21
	v_lshlrev_b32_e32 v132, 16, v21
	v_and_b32_e32 v21, 0xffff0000, v22
	v_lshlrev_b32_e32 v20, 16, v22
	v_and_b32_e32 v135, 0xffff0000, v23
	v_lshlrev_b32_e32 v134, 16, v23
	v_pk_add_f32 v[22:23], v[124:125], v[130:131]
	v_pk_add_f32 v[124:125], v[126:127], v[132:133]
	s_waitcnt vmcnt(13)
	v_and_b32_e32 v127, 0xffff0000, v8
	v_lshlrev_b32_e32 v126, 16, v8
	v_and_b32_e32 v131, 0xffff0000, v9
	v_lshlrev_b32_e32 v130, 16, v9
	v_and_b32_e32 v9, 0xffff0000, v10
	v_lshlrev_b32_e32 v8, 16, v10
	v_and_b32_e32 v133, 0xffff0000, v11
	v_lshlrev_b32_e32 v132, 16, v11
	v_pk_add_f32 v[4:5], v[4:5], v[20:21]
	v_pk_add_f32 v[10:11], v[128:129], v[134:135]
	s_waitcnt vmcnt(12)
	v_and_b32_e32 v21, 0xffff0000, v100
	v_lshlrev_b32_e32 v20, 16, v100
	v_and_b32_e32 v129, 0xffff0000, v101
	v_lshlrev_b32_e32 v128, 16, v101
	v_and_b32_e32 v101, 0xffff0000, v102
	v_lshlrev_b32_e32 v100, 16, v102
	v_and_b32_e32 v135, 0xffff0000, v103
	v_lshlrev_b32_e32 v134, 16, v103
	v_pk_add_f32 v[8:9], v[8:9], v[100:101]
	v_pk_add_f32 v[100:101], v[132:133], v[134:135]
	v_pk_add_f32 v[4:5], v[4:5], v[8:9]
	v_lshlrev_b32_e32 v6, 16, v0
	v_and_b32_e32 v7, 0xffff0000, v0
	v_pk_add_f32 v[8:9], v[10:11], v[100:101]
	s_waitcnt vmcnt(10)
	v_pk_fma_f32 v[80:81], v[108:109], v[4:5], v[80:81]
	s_waitcnt vmcnt(9)
	v_lshlrev_b32_e32 v4, 16, v24
	v_and_b32_e32 v5, 0xffff0000, v24
	v_pk_fma_f32 v[82:83], v[110:111], v[8:9], v[82:83]
	s_waitcnt vmcnt(8)
	v_lshlrev_b32_e32 v8, 16, v16
	v_and_b32_e32 v9, 0xffff0000, v16
	v_pk_add_f32 v[4:5], v[6:7], v[4:5]
	s_waitcnt vmcnt(7)
	v_lshlrev_b32_e32 v6, 16, v12
	v_and_b32_e32 v7, 0xffff0000, v12
	v_pk_add_f32 v[6:7], v[8:9], v[6:7]
	v_lshlrev_b32_e32 v0, 16, v1
	v_and_b32_e32 v1, 0xffff0000, v1
	v_lshlrev_b32_e32 v8, 16, v25
	v_and_b32_e32 v9, 0xffff0000, v25
	v_lshlrev_b32_e32 v10, 16, v17
	v_and_b32_e32 v11, 0xffff0000, v17
	v_pk_add_f32 v[0:1], v[0:1], v[8:9]
	v_lshlrev_b32_e32 v8, 16, v13
	v_and_b32_e32 v9, 0xffff0000, v13
	v_pk_add_f32 v[12:13], v[10:11], v[8:9]
	v_lshlrev_b32_e32 v24, 16, v18
	v_pk_add_f32 v[0:1], v[0:1], v[12:13]
	v_lshlrev_b32_e32 v12, 16, v26
	s_waitcnt vmcnt(6)
	v_pk_fma_f32 v[78:79], v[34:35], v[0:1], v[78:79]
	v_lshlrev_b32_e32 v0, 16, v2
	v_and_b32_e32 v1, 0xffff0000, v2
	v_and_b32_e32 v13, 0xffff0000, v26
	v_and_b32_e32 v25, 0xffff0000, v18
	v_pk_add_f32 v[0:1], v[0:1], v[12:13]
	v_lshlrev_b32_e32 v12, 16, v14
	v_and_b32_e32 v13, 0xffff0000, v14
	v_pk_add_f32 v[12:13], v[24:25], v[12:13]
	v_pk_add_f32 v[4:5], v[4:5], v[6:7]
	v_lshlrev_b32_e32 v2, 16, v3
	v_and_b32_e32 v3, 0xffff0000, v3
	v_lshlrev_b32_e32 v16, 16, v27
	v_and_b32_e32 v17, 0xffff0000, v27
	v_lshlrev_b32_e32 v18, 16, v19
	v_and_b32_e32 v19, 0xffff0000, v19
	v_pk_add_f32 v[0:1], v[0:1], v[12:13]
	v_lshlrev_b32_e32 v12, 16, v15
	v_and_b32_e32 v13, 0xffff0000, v15
	v_pk_add_f32 v[20:21], v[126:127], v[20:21]
	v_pk_add_f32 v[102:103], v[130:131], v[128:129]
	v_pk_fma_f32 v[76:77], v[32:33], v[4:5], v[76:77]
	global_load_dwordx4 v[4:7], v97, s[6:7] offset:16
	s_waitcnt vmcnt(4)
	v_pk_fma_f32 v[72:73], v[112:113], v[0:1], v[72:73]
	v_pk_add_f32 v[0:1], v[2:3], v[16:17]
	v_pk_add_f32 v[2:3], v[18:19], v[12:13]
	v_pk_add_f32 v[20:21], v[22:23], v[20:21]
	v_pk_add_f32 v[22:23], v[124:125], v[102:103]
	v_pk_add_f32 v[0:1], v[0:1], v[2:3]
	v_pk_fma_f32 v[84:85], v[104:105], v[20:21], v[84:85]
	v_pk_fma_f32 v[86:87], v[106:107], v[22:23], v[86:87]
	global_load_dwordx4 v[8:11], v[88:89], off offset:3072 nt
	global_load_dwordx4 v[20:23], v[90:91], off offset:3072 nt
	global_load_dwordx4 v[32:35], v[92:93], off offset:3072 nt
	v_pk_fma_f32 v[74:75], v[114:115], v[0:1], v[74:75]
	global_load_dwordx4 v[0:3], v98, s[6:7] offset:16
	global_load_dwordx4 v[88:91], v[94:95], off offset:3072 nt
	v_lshlrev_b32_e32 v12, 16, v28
	global_load_dwordx4 v[92:95], v98, s[6:7]
	v_and_b32_e32 v13, 0xffff0000, v28
	v_lshlrev_b32_e32 v14, 16, v36
	v_and_b32_e32 v15, 0xffff0000, v36
	s_waitcnt vmcnt(9)
	v_lshlrev_b32_e32 v16, 16, v40
	v_and_b32_e32 v17, 0xffff0000, v40
	v_pk_add_f32 v[12:13], v[12:13], v[14:15]
	s_waitcnt vmcnt(7)
	v_lshlrev_b32_e32 v14, 16, v120
	v_and_b32_e32 v15, 0xffff0000, v120
	v_pk_add_f32 v[14:15], v[16:17], v[14:15]
	v_lshlrev_b32_e32 v16, 16, v121
	v_pk_add_f32 v[12:13], v[12:13], v[14:15]
	v_lshlrev_b32_e32 v14, 16, v37
	v_pk_fma_f32 v[68:69], v[116:117], v[12:13], v[68:69]
	v_lshlrev_b32_e32 v12, 16, v29
	v_and_b32_e32 v13, 0xffff0000, v29
	v_and_b32_e32 v15, 0xffff0000, v37
	v_pk_add_f32 v[12:13], v[12:13], v[14:15]
	v_lshlrev_b32_e32 v14, 16, v41
	v_and_b32_e32 v15, 0xffff0000, v41
	v_and_b32_e32 v17, 0xffff0000, v121
	v_pk_add_f32 v[14:15], v[14:15], v[16:17]
	v_lshlrev_b32_e32 v24, 16, v42
	v_pk_add_f32 v[12:13], v[12:13], v[14:15]
	v_lshlrev_b32_e32 v14, 16, v38
	v_pk_fma_f32 v[70:71], v[118:119], v[12:13], v[70:71]
	v_lshlrev_b32_e32 v12, 16, v30
	v_and_b32_e32 v13, 0xffff0000, v30
	v_and_b32_e32 v15, 0xffff0000, v38
	v_and_b32_e32 v25, 0xffff0000, v42
	v_pk_add_f32 v[12:13], v[12:13], v[14:15]
	v_lshlrev_b32_e32 v14, 16, v122
	v_and_b32_e32 v15, 0xffff0000, v122
	v_pk_add_f32 v[14:15], v[24:25], v[14:15]
	v_lshlrev_b32_e32 v16, 16, v31
	v_and_b32_e32 v17, 0xffff0000, v31
	v_lshlrev_b32_e32 v18, 16, v39
	v_and_b32_e32 v19, 0xffff0000, v39
	v_lshlrev_b32_e32 v24, 16, v43
	v_and_b32_e32 v25, 0xffff0000, v43
	v_pk_add_f32 v[12:13], v[12:13], v[14:15]
	v_lshlrev_b32_e32 v14, 16, v123
	v_and_b32_e32 v15, 0xffff0000, v123
	s_waitcnt vmcnt(6)
	v_pk_fma_f32 v[64:65], v[4:5], v[12:13], v[64:65]
	v_pk_add_f32 v[4:5], v[16:17], v[18:19]
	v_pk_add_f32 v[12:13], v[24:25], v[14:15]
	s_waitcnt vmcnt(1)
	v_lshlrev_b32_e32 v14, 16, v88
	v_pk_add_f32 v[4:5], v[4:5], v[12:13]
	v_lshlrev_b32_e32 v12, 16, v32
	v_pk_fma_f32 v[66:67], v[6:7], v[4:5], v[66:67]
	v_lshlrev_b32_e32 v4, 16, v8
	v_and_b32_e32 v5, 0xffff0000, v8
	v_lshlrev_b32_e32 v6, 16, v20
	v_and_b32_e32 v7, 0xffff0000, v20
	v_and_b32_e32 v13, 0xffff0000, v32
	v_and_b32_e32 v15, 0xffff0000, v88
	v_pk_add_f32 v[4:5], v[4:5], v[6:7]
	v_pk_add_f32 v[6:7], v[12:13], v[14:15]
	v_lshlrev_b32_e32 v8, 16, v33
	v_pk_add_f32 v[4:5], v[4:5], v[6:7]
	v_lshlrev_b32_e32 v6, 16, v21
	s_waitcnt vmcnt(0)
	v_pk_fma_f32 v[56:57], v[92:93], v[4:5], v[56:57]
	v_lshlrev_b32_e32 v4, 16, v9
	v_and_b32_e32 v5, 0xffff0000, v9
	v_and_b32_e32 v7, 0xffff0000, v21
	v_and_b32_e32 v9, 0xffff0000, v33
	v_lshlrev_b32_e32 v12, 16, v89
	v_and_b32_e32 v13, 0xffff0000, v89
	v_pk_add_f32 v[4:5], v[4:5], v[6:7]
	v_pk_add_f32 v[6:7], v[8:9], v[12:13]
	v_lshlrev_b32_e32 v8, 16, v34
	v_pk_add_f32 v[4:5], v[4:5], v[6:7]
	v_lshlrev_b32_e32 v6, 16, v22
	v_pk_fma_f32 v[60:61], v[94:95], v[4:5], v[60:61]
	v_lshlrev_b32_e32 v4, 16, v10
	v_and_b32_e32 v5, 0xffff0000, v10
	v_and_b32_e32 v7, 0xffff0000, v22
	v_and_b32_e32 v9, 0xffff0000, v34
	v_lshlrev_b32_e32 v12, 16, v90
	v_and_b32_e32 v13, 0xffff0000, v90
	v_pk_add_f32 v[4:5], v[4:5], v[6:7]
	v_pk_add_f32 v[6:7], v[8:9], v[12:13]
	v_lshlrev_b32_e32 v8, 16, v91
	v_pk_add_f32 v[4:5], v[4:5], v[6:7]
	v_lshlrev_b32_e32 v6, 16, v35
	v_pk_fma_f32 v[58:59], v[0:1], v[4:5], v[58:59]
	v_lshlrev_b32_e32 v0, 16, v11
	v_and_b32_e32 v1, 0xffff0000, v11
	v_lshlrev_b32_e32 v4, 16, v23
	v_and_b32_e32 v5, 0xffff0000, v23
	v_and_b32_e32 v7, 0xffff0000, v35
	v_and_b32_e32 v9, 0xffff0000, v91
	v_pk_add_f32 v[0:1], v[0:1], v[4:5]
	v_pk_add_f32 v[4:5], v[6:7], v[8:9]
	s_nop 0
	v_pk_add_f32 v[0:1], v[0:1], v[4:5]
	s_nop 0
	v_pk_fma_f32 v[62:63], v[2:3], v[0:1], v[62:63]
	s_branch .LBB0_1229
